# stack: pk_add row sums + hand-written compressed pass 1 and pass 2 paths for fully valid tiles
# speedup vs baseline: 1.0045x; 1.0002x over previous
; __device__ __forceinline__ void nsa_wg_task(bf16_t* zb, const bf16_t* kcb, const bf16_t* vctb, const bf16_t* vst, const bf16_t* vwt, int g, int T0, float* accb, LAS unsigned char* lds, int wave, int lane, int tid) {
;     ...
;         if (i < nc) {
;             const int kb0 = i * 64; const bool n0 = kb0 < nv[0], n1 = kb0 < nv[1];
;             if (n0 || n1) { nsa_loadk(kbuf, offk0, offk1, ka, kb);
; #pragma unroll
;                 for (int r = 0; r < 2; ++r) if (r == 0 ? n0 : n1) { nsa_scores(ka, kb, q0[r], q1[r], S);
; #pragma unroll
;                     for (int st = 0; st < 4; ++st)
; #pragma unroll
;                         for (int j = 0; j < 4; ++j) { const float e = __builtin_amdgcn_exp2f(S[st][j]); l[r] += (kb0 + st * 16 + 4 * fq + j < nvl[r]) ? e : 0.f; } } }
.Lp1_fast:
	s_waitcnt lgkmcnt(0)
	v_add_u32_e32 v124, s45, v195
	v_add_u32_e32 v125, s45, v196
	ds_read_b128 v[132:135], v124
	ds_read_b128 v[136:139], v124 offset:2048
	ds_read_b128 v[140:143], v124 offset:4096
	ds_read_b128 v[144:147], v124 offset:6144
	ds_read_b128 v[148:151], v125
	ds_read_b128 v[152:155], v125 offset:2048
	ds_read_b128 v[116:119], v125 offset:4096
	ds_read_b128 v[120:123], v125 offset:6144
	s_waitcnt lgkmcnt(0)
	v_mfma_f32_16x16x32_bf16 v[16:19], v[132:135], v[60:63], 0
	v_mfma_f32_16x16x32_bf16 v[20:23], v[136:139], v[60:63], 0
	v_mfma_f32_16x16x32_bf16 v[24:27], v[140:143], v[60:63], 0
	v_mfma_f32_16x16x32_bf16 v[28:31], v[144:147], v[60:63], 0
	v_mfma_f32_16x16x32_bf16 v[16:19], v[148:151], v[72:75], v[16:19]
	v_mfma_f32_16x16x32_bf16 v[20:23], v[152:155], v[72:75], v[20:23]
	v_mfma_f32_16x16x32_bf16 v[24:27], v[116:119], v[72:75], v[24:27]
	v_mfma_f32_16x16x32_bf16 v[28:31], v[120:123], v[72:75], v[28:31]
	s_nop 7
	v_exp_f32_e32 v16, v16
	v_exp_f32_e32 v17, v17
	v_mfma_f32_16x16x32_bf16 v[32:35], v[132:135], v[76:79], 0
	v_exp_f32_e32 v18, v18
	v_exp_f32_e32 v19, v19
	v_mfma_f32_16x16x32_bf16 v[36:39], v[136:139], v[76:79], 0
	v_exp_f32_e32 v20, v20
	v_exp_f32_e32 v21, v21
	v_mfma_f32_16x16x32_bf16 v[40:43], v[140:143], v[76:79], 0
	v_exp_f32_e32 v22, v22
	v_exp_f32_e32 v23, v23
	v_mfma_f32_16x16x32_bf16 v[44:47], v[144:147], v[76:79], 0
	v_exp_f32_e32 v24, v24
	v_exp_f32_e32 v25, v25
	v_mfma_f32_16x16x32_bf16 v[32:35], v[148:151], v[80:83], v[32:35]
	v_exp_f32_e32 v26, v26
	v_exp_f32_e32 v27, v27
	v_mfma_f32_16x16x32_bf16 v[36:39], v[152:155], v[80:83], v[36:39]
	v_exp_f32_e32 v28, v28
	v_exp_f32_e32 v29, v29
	v_mfma_f32_16x16x32_bf16 v[40:43], v[116:119], v[80:83], v[40:43]
	v_exp_f32_e32 v30, v30
	v_exp_f32_e32 v31, v31
	v_mfma_f32_16x16x32_bf16 v[44:47], v[120:123], v[80:83], v[44:47]
	v_pk_add_f32 v[124:125], v[16:17], v[18:19]
	v_pk_add_f32 v[126:127], v[20:21], v[22:23]
	v_pk_add_f32 v[128:129], v[24:25], v[26:27]
	v_pk_add_f32 v[252:253], v[28:29], v[30:31]
	v_pk_add_f32 v[124:125], v[124:125], v[126:127]
	v_pk_add_f32 v[128:129], v[128:129], v[252:253]
	v_pk_add_f32 v[124:125], v[124:125], v[128:129]
	v_add_f32_e32 v124, v124, v125
	v_add_f32_e32 v172, v172, v124
	s_nop 7
	v_exp_f32_e32 v32, v32
	v_exp_f32_e32 v33, v33
	v_exp_f32_e32 v34, v34
	v_exp_f32_e32 v35, v35
	v_exp_f32_e32 v36, v36
	v_exp_f32_e32 v37, v37
	v_exp_f32_e32 v38, v38
	v_exp_f32_e32 v39, v39
	v_exp_f32_e32 v40, v40
	v_exp_f32_e32 v41, v41
	v_exp_f32_e32 v42, v42
	v_exp_f32_e32 v43, v43
	v_exp_f32_e32 v44, v44
	v_exp_f32_e32 v45, v45
	v_exp_f32_e32 v46, v46
	v_exp_f32_e32 v47, v47
	v_pk_add_f32 v[124:125], v[32:33], v[34:35]
	v_pk_add_f32 v[126:127], v[36:37], v[38:39]
	v_pk_add_f32 v[128:129], v[40:41], v[42:43]
	v_pk_add_f32 v[252:253], v[44:45], v[46:47]
	v_pk_add_f32 v[124:125], v[124:125], v[126:127]
	v_pk_add_f32 v[128:129], v[128:129], v[252:253]
	v_pk_add_f32 v[124:125], v[124:125], v[128:129]
	v_add_f32_e32 v124, v124, v125
	v_add_f32_e32 v173, v173, v124
	s_branch .LBB0_340

; __device__ __forceinline__ void nsa_wg_task(bf16_t* zb, const bf16_t* kcb, const bf16_t* vctb, const bf16_t* vst, const bf16_t* vwt, int g, int T0, float* accb, LAS unsigned char* lds, int wave, int lane, int tid) {
;     ...
;         if (i < nc) {
;             const int kb0 = i * 64; const bool n0 = kb0 < nv[0], n1 = kb0 < nv[1];
;             if (n0 || n1) { nsa_loadk(kbuf, offk0, offk1, ka, kb);
.LBB0_335:
	s_lshl_b32 s2, s44, 6
	s_cmp_lt_u32 s2, s0
	s_cselect_b64 s[22:23], -1, 0
	s_cmp_lt_u32 s2, s86
	s_cselect_b64 s[20:21], -1, 0
	s_or_b64 s[24:25], s[22:23], s[20:21]
	s_add_i32 s94, s2, 64
	s_sub_i32 s95, s88, 31
	s_ashr_i32 s95, s95, 4
	s_add_i32 s95, s95, 1
	s_cmp_le_i32 s94, s95
	s_cbranch_scc0 .Lp1_slow
	s_sub_i32 s95, s89, 31
	s_ashr_i32 s95, s95, 4
	s_add_i32 s95, s95, 1
	s_cmp_le_i32 s94, s95
	s_cbranch_scc1 .Lp1_fast
.Lp1_slow:
	s_andn2_b64 vcc, exec, s[24:25]
	s_cbranch_vccnz .LBB0_340
	s_waitcnt lgkmcnt(0)
	v_add_u32_e32 v16, s45, v195
	v_add_u32_e32 v17, s45, v196
	ds_read_b128 v[40:43], v16
	ds_read_b128 v[36:39], v16 offset:2048
	ds_read_b128 v[44:47], v17
	ds_read_b128 v[28:31], v17 offset:2048
	ds_read_b128 v[32:35], v16 offset:4096
	ds_read_b128 v[24:27], v16 offset:6144
	ds_read_b128 v[20:23], v17 offset:4096
	ds_read_b128 v[16:19], v17 offset:6144
	v_add_u32_e32 v48, s2, v166
	s_andn2_b64 vcc, exec, s[22:23]
	v_or_b32_e32 v51, 1, v48
	v_or_b32_e32 v50, 2, v48
	v_or_b32_e32 v49, 3, v48
	s_cbranch_vccnz .LBB0_338
	s_waitcnt lgkmcnt(0)
	v_mfma_f32_16x16x32_bf16 v[52:55], v[40:43], v[60:63], 0
	v_cmp_lt_i32_e32 vcc, v48, v161
	v_mfma_f32_16x16x32_bf16 v[52:55], v[44:47], v[72:75], v[52:55]
	v_mfma_f32_16x16x32_bf16 v[116:119], v[36:39], v[60:63], 0
	v_mfma_f32_16x16x32_bf16 v[120:123], v[32:35], v[60:63], 0
	s_nop 5
	v_exp_f32_e32 v52, v52
	v_exp_f32_e32 v53, v53
	v_exp_f32_e32 v54, v54
	v_exp_f32_e32 v124, v55
	v_cndmask_b32_e32 v52, 0, v52, vcc
	v_cmp_lt_i32_e32 vcc, v51, v161
	v_add_f32_e32 v52, v172, v52
	v_mfma_f32_16x16x32_bf16 v[120:123], v[20:23], v[72:75], v[120:123]
	v_cndmask_b32_e32 v53, 0, v53, vcc
	v_cmp_lt_i32_e32 vcc, v50, v161
	v_add_f32_e32 v52, v53, v52
	s_nop 0
	v_cndmask_b32_e32 v53, 0, v54, vcc
	v_add_f32_e32 v65, v53, v52
	v_mfma_f32_16x16x32_bf16 v[52:55], v[28:31], v[72:75], v[116:119]
	v_cmp_lt_i32_e32 vcc, v49, v161
	s_nop 1
	v_cndmask_b32_e32 v116, 0, v124, vcc
	v_cmp_lt_i32_e32 vcc, v48, v212
	s_nop 2
	v_exp_f32_e32 v52, v52
	v_exp_f32_e32 v53, v53
	v_add_f32_e32 v65, v116, v65
	v_exp_f32_e32 v54, v54
	v_cndmask_b32_e32 v52, 0, v52, vcc
	v_cmp_lt_i32_e32 vcc, v48, v213
	v_add_f32_e32 v52, v52, v65
	v_mfma_f32_16x16x32_bf16 v[116:119], v[24:27], v[60:63], 0
	v_cndmask_b32_e32 v53, 0, v53, vcc
	v_add_f32_e32 v52, v53, v52
	v_exp_f32_e32 v53, v55
	v_cmp_lt_i32_e32 vcc, v48, v214
	v_mfma_f32_16x16x32_bf16 v[116:119], v[16:19], v[72:75], v[116:119]
	s_nop 0
	v_cndmask_b32_e32 v54, 0, v54, vcc
	v_cmp_lt_i32_e32 vcc, v48, v215
	v_add_f32_e32 v52, v54, v52
	v_exp_f32_e32 v54, v120
	v_cndmask_b32_e32 v53, 0, v53, vcc
	v_add_f32_e32 v52, v53, v52
	v_exp_f32_e32 v53, v121
	v_cmp_lt_i32_e32 vcc, v48, v216
	s_nop 1
	v_cndmask_b32_e32 v54, 0, v54, vcc
	v_cmp_lt_i32_e32 vcc, v48, v217
	v_add_f32_e32 v52, v54, v52
	v_exp_f32_e32 v54, v122
	v_cndmask_b32_e32 v53, 0, v53, vcc
	v_add_f32_e32 v52, v53, v52
	v_exp_f32_e32 v53, v123
	v_cmp_lt_i32_e32 vcc, v48, v218
	s_nop 1
	v_cndmask_b32_e32 v54, 0, v54, vcc
	v_cmp_lt_i32_e32 vcc, v48, v219
	v_add_f32_e32 v52, v54, v52
	v_exp_f32_e32 v54, v116
	v_cndmask_b32_e32 v53, 0, v53, vcc
	v_add_f32_e32 v52, v53, v52
	v_exp_f32_e32 v53, v117
	v_cmp_lt_i32_e32 vcc, v48, v220
	s_nop 1
	v_cndmask_b32_e32 v54, 0, v54, vcc
	v_cmp_lt_i32_e32 vcc, v48, v221
	v_add_f32_e32 v52, v54, v52
	v_exp_f32_e32 v54, v118
	v_cndmask_b32_e32 v53, 0, v53, vcc
	v_add_f32_e32 v52, v53, v52
	v_exp_f32_e32 v53, v119
	v_cmp_lt_i32_e32 vcc, v48, v222
	s_nop 1
	v_cndmask_b32_e32 v54, 0, v54, vcc
	v_cmp_lt_i32_e32 vcc, v48, v223
	v_add_f32_e32 v52, v54, v52
	s_nop 0
	v_cndmask_b32_e32 v53, 0, v53, vcc
	v_add_f32_e32 v172, v53, v52
